# stacks: final rmsnorm loop-invariant weight preload; wf8 epilogue copy-out LDS reads batched
# baseline (speedup 1.0000x reference)
.LBB0_510:
	v_mov_b32_e32 v128, v205
	s_waitcnt vmcnt(0)
	v_mov_b32_e32 v130, v205
	v_and_b32_e32 v131, 31, v128
	v_lshrrev_b32_e32 v128, 2, v128
	v_and_b32_e32 v128, 8, v128
	s_movk_i32 s4, 0xffc0
	v_cvt_pk_bf16_f32 v0, v0, v1
	v_and_or_b32 v128, v130, s4, v128
	v_mad_u32_u24 v128, v131, s47, v128
	v_cvt_pk_bf16_f32 v1, v2, v3
	v_cvt_pk_bf16_f32 v2, v4, v5
	v_cvt_pk_bf16_f32 v3, v6, v7
	v_add_u32_e32 v4, 0xe800, v128
	v_cvt_pk_bf16_f32 v112, v112, v113
	v_cvt_pk_bf16_f32 v113, v114, v115
	v_cvt_pk_bf16_f32 v114, v116, v117
	v_cvt_pk_bf16_f32 v115, v118, v119
	v_cvt_pk_bf16_f32 v96, v96, v97
	v_cvt_pk_bf16_f32 v97, v98, v99
	v_cvt_pk_bf16_f32 v98, v100, v101
	v_cvt_pk_bf16_f32 v99, v102, v103
	v_add_u32_e32 v100, 0x2000, v128
	v_cvt_pk_bf16_f32 v80, v80, v81
	v_cvt_pk_bf16_f32 v81, v82, v83
	v_cvt_pk_bf16_f32 v82, v84, v85
	v_cvt_pk_bf16_f32 v83, v86, v87
	v_add_u32_e32 v84, 0x4000, v128
	v_cvt_pk_bf16_f32 v64, v64, v65
	v_cvt_pk_bf16_f32 v65, v66, v67
	v_cvt_pk_bf16_f32 v66, v68, v69
	v_cvt_pk_bf16_f32 v67, v70, v71
	v_add_u32_e32 v68, 0x6000, v128
	v_cvt_pk_bf16_f32 v48, v48, v49
	v_cvt_pk_bf16_f32 v49, v50, v51
	v_cvt_pk_bf16_f32 v50, v52, v53
	v_cvt_pk_bf16_f32 v51, v54, v55
	v_add_u32_e32 v52, 0x8800, v128
	v_cvt_pk_bf16_f32 v32, v32, v33
	v_cvt_pk_bf16_f32 v33, v34, v35
	v_cvt_pk_bf16_f32 v34, v36, v37
	v_cvt_pk_bf16_f32 v35, v38, v39
	v_add_u32_e32 v36, 0xa800, v128
	v_cvt_pk_bf16_f32 v16, v16, v17
	v_cvt_pk_bf16_f32 v17, v18, v19
	v_cvt_pk_bf16_f32 v18, v20, v21
	v_cvt_pk_bf16_f32 v19, v22, v23
	v_add_u32_e32 v20, 0xc800, v128
	ds_write2_b64 v4, v[0:1], v[2:3] offset0:192 offset1:194
	v_cvt_pk_bf16_f32 v0, v8, v9
	v_cvt_pk_bf16_f32 v1, v10, v11
	v_cvt_pk_bf16_f32 v2, v12, v13
	v_cvt_pk_bf16_f32 v3, v14, v15
	ds_write2_b64 v128, v[112:113], v[114:115] offset1:2
	v_cvt_pk_bf16_f32 v112, v120, v121
	v_cvt_pk_bf16_f32 v113, v122, v123
	v_cvt_pk_bf16_f32 v114, v124, v125
	v_cvt_pk_bf16_f32 v115, v126, v127
	ds_write2_b64 v100, v[96:97], v[98:99] offset0:64 offset1:66
	v_cvt_pk_bf16_f32 v96, v104, v105
	v_cvt_pk_bf16_f32 v97, v106, v107
	v_cvt_pk_bf16_f32 v98, v108, v109
	v_cvt_pk_bf16_f32 v99, v110, v111
	ds_write2_b64 v84, v[80:81], v[82:83] offset0:128 offset1:130
	v_cvt_pk_bf16_f32 v80, v88, v89
	v_cvt_pk_bf16_f32 v81, v90, v91
	v_cvt_pk_bf16_f32 v82, v92, v93
	v_cvt_pk_bf16_f32 v83, v94, v95
	ds_write2_b64 v68, v[64:65], v[66:67] offset0:192 offset1:194
	v_cvt_pk_bf16_f32 v64, v72, v73
	v_cvt_pk_bf16_f32 v65, v74, v75
	v_cvt_pk_bf16_f32 v66, v76, v77
	v_cvt_pk_bf16_f32 v67, v78, v79
	ds_write2_b64 v52, v[48:49], v[50:51] offset1:2
	v_cvt_pk_bf16_f32 v48, v56, v57
	v_cvt_pk_bf16_f32 v49, v58, v59
	v_cvt_pk_bf16_f32 v50, v60, v61
	v_cvt_pk_bf16_f32 v51, v62, v63
	ds_write2_b64 v36, v[32:33], v[34:35] offset0:64 offset1:66
	v_cvt_pk_bf16_f32 v32, v40, v41
	v_cvt_pk_bf16_f32 v33, v42, v43
	v_cvt_pk_bf16_f32 v34, v44, v45
	v_cvt_pk_bf16_f32 v35, v46, v47
	ds_write2_b64 v20, v[16:17], v[18:19] offset0:128 offset1:130
	v_cvt_pk_bf16_f32 v16, v24, v25
	v_cvt_pk_bf16_f32 v17, v26, v27
	v_cvt_pk_bf16_f32 v18, v28, v29
	v_cvt_pk_bf16_f32 v19, v30, v31
	ds_write2_b64 v4, v[0:1], v[2:3] offset0:196 offset1:198
	v_mov_b32_e32 v0, v205
	ds_write2_b64 v128, v[112:113], v[114:115] offset0:4 offset1:6
	ds_write2_b64 v100, v[96:97], v[98:99] offset0:68 offset1:70
	ds_write2_b64 v84, v[80:81], v[82:83] offset0:132 offset1:134
	ds_write2_b64 v68, v[64:65], v[66:67] offset0:196 offset1:198
	ds_write2_b64 v52, v[48:49], v[50:51] offset0:4 offset1:6
	ds_write2_b64 v36, v[32:33], v[34:35] offset0:68 offset1:70
	ds_write2_b64 v20, v[16:17], v[18:19] offset0:132 offset1:134
	s_waitcnt lgkmcnt(0)
	s_barrier
	s_sub_i32 s4, 0x1230, s46
	v_lshlrev_b32_e32 v1, 3, v0
	v_and_b32_e32 v1, 0x78, v1
	v_cmp_gt_i32_e32 vcc, s4, v1
	s_and_saveexec_b64 s[4:5], vcc
	s_cbranch_execz .LBB0_275
	s_mul_hi_i32 s6, s2, 0x2480
	s_mulk_i32 s2, 0x2480
	s_add_u32 s2, s57, s2
	s_addc_u32 s8, s58, s6
	s_ashr_i32 s47, s46, 31
	s_lshl_b64 s[6:7], s[46:47], 1
	s_add_u32 s6, s2, s6
	s_movk_i32 s47, 0x110
	s_addc_u32 s7, s8, s7
	v_lshlrev_b32_e32 v128, 1, v1
	v_ashrrev_i32_e32 v1, 4, v0
	v_lshl_add_u64 v[6:7], s[6:7], 0, v[128:129]
	v_mad_u64_u32 v[2:3], s[6:7], v1, s47, v[128:129]
	v_mad_i64_i32 v[8:9], s[6:7], v1, s33, v[6:7]
	v_mov_b32_e32 v80, v2
	s_mov_b64 s[100:101], 0x24800
	ds_read_b128 v[16:19], v80
	ds_read_b128 v[20:23], v80 offset:4352
	ds_read_b128 v[24:27], v80 offset:8704
	ds_read_b128 v[28:31], v80 offset:13056
	ds_read_b128 v[32:35], v80 offset:17408
	ds_read_b128 v[36:39], v80 offset:21760
	ds_read_b128 v[40:43], v80 offset:26112
	ds_read_b128 v[44:47], v80 offset:30464
	ds_read_b128 v[48:51], v80 offset:34816
	ds_read_b128 v[52:55], v80 offset:39168
	ds_read_b128 v[56:59], v80 offset:43520
	ds_read_b128 v[60:63], v80 offset:47872
	ds_read_b128 v[64:67], v80 offset:52224
	ds_read_b128 v[68:71], v80 offset:56576
	ds_read_b128 v[72:75], v80 offset:60928
	ds_read_b128 v[76:79], v80 offset:65280
	s_waitcnt lgkmcnt(15)
	global_store_dwordx4 v[8:9], v[16:19], off
	v_lshl_add_u64 v[8:9], v[8:9], 0, s[100:101]
	s_waitcnt lgkmcnt(14)
	global_store_dwordx4 v[8:9], v[20:23], off
	v_lshl_add_u64 v[8:9], v[8:9], 0, s[100:101]
	s_waitcnt lgkmcnt(13)
	global_store_dwordx4 v[8:9], v[24:27], off
	v_lshl_add_u64 v[8:9], v[8:9], 0, s[100:101]
	s_waitcnt lgkmcnt(12)
	global_store_dwordx4 v[8:9], v[28:31], off
	v_lshl_add_u64 v[8:9], v[8:9], 0, s[100:101]
	s_waitcnt lgkmcnt(11)
	global_store_dwordx4 v[8:9], v[32:35], off
	v_lshl_add_u64 v[8:9], v[8:9], 0, s[100:101]
	s_waitcnt lgkmcnt(10)
	global_store_dwordx4 v[8:9], v[36:39], off
	v_lshl_add_u64 v[8:9], v[8:9], 0, s[100:101]
	s_waitcnt lgkmcnt(9)
	global_store_dwordx4 v[8:9], v[40:43], off
	v_lshl_add_u64 v[8:9], v[8:9], 0, s[100:101]
	s_waitcnt lgkmcnt(8)
	global_store_dwordx4 v[8:9], v[44:47], off
	v_lshl_add_u64 v[8:9], v[8:9], 0, s[100:101]
	s_waitcnt lgkmcnt(7)
	global_store_dwordx4 v[8:9], v[48:51], off
	v_lshl_add_u64 v[8:9], v[8:9], 0, s[100:101]
	s_waitcnt lgkmcnt(6)
	global_store_dwordx4 v[8:9], v[52:55], off
	v_lshl_add_u64 v[8:9], v[8:9], 0, s[100:101]
	s_waitcnt lgkmcnt(5)
	global_store_dwordx4 v[8:9], v[56:59], off
	v_lshl_add_u64 v[8:9], v[8:9], 0, s[100:101]
	s_waitcnt lgkmcnt(4)
	global_store_dwordx4 v[8:9], v[60:63], off
	v_lshl_add_u64 v[8:9], v[8:9], 0, s[100:101]
	s_waitcnt lgkmcnt(3)
	global_store_dwordx4 v[8:9], v[64:67], off
	v_lshl_add_u64 v[8:9], v[8:9], 0, s[100:101]
	s_waitcnt lgkmcnt(2)
	global_store_dwordx4 v[8:9], v[68:71], off
	v_lshl_add_u64 v[8:9], v[8:9], 0, s[100:101]
	s_waitcnt lgkmcnt(1)
	global_store_dwordx4 v[8:9], v[72:75], off
	v_lshl_add_u64 v[8:9], v[8:9], 0, s[100:101]
	s_waitcnt lgkmcnt(0)
	global_store_dwordx4 v[8:9], v[76:79], off
	s_branch .LBB0_275

.LBB0_1789:
	v_mul_f32_e32 v112, 0xbfb8aa3b, v112
	v_mul_f32_e32 v113, 0xbfb8aa3b, v113
	v_exp_f32_e32 v112, v112
	v_exp_f32_e32 v113, v113
	v_mov_b32_e32 v128, v205
	s_lshl_b32 s2, s6, 8
	s_add_i32 s7, s15, 0x600
	s_cmpk_lt_i32 s15, 0x800
	s_waitcnt vmcnt(0)
	v_mov_b32_e32 v130, v205
	v_and_b32_e32 v131, 31, v128
	v_lshrrev_b32_e32 v128, 2, v128
	s_cselect_b32 s8, s15, s7
	v_and_b32_e32 v128, 8, v128
	s_movk_i32 s7, 0xffc0
	v_pk_add_f32 v[112:113], v[112:113], 1.0 op_sel_hi:[1,0]
	v_and_or_b32 v128, v130, s7, v128
	v_mad_u32_u24 v128, v131, s47, v128
	v_mul_f32_e32 v96, 0xbfb8aa3b, v96
	v_mul_f32_e32 v97, 0xbfb8aa3b, v97
	v_exp_f32_e32 v96, v96
	v_rcp_f32_e32 v113, v113
	s_nop 0
	v_exp_f32_e32 v97, v97
	v_mul_f32_e32 v80, 0xbfb8aa3b, v80
	v_mul_f32_e32 v81, 0xbfb8aa3b, v81
	v_rcp_f32_e32 v112, v112
	s_nop 0
	v_cvt_pk_bf16_f32 v112, v112, v113
	v_mul_f32_e32 v113, 0xbfb8aa3b, v114
	v_exp_f32_e32 v114, v113
	v_mul_f32_e32 v113, 0xbfb8aa3b, v115
	v_exp_f32_e32 v115, v113
	v_pk_add_f32 v[96:97], v[96:97], 1.0 op_sel_hi:[1,0]
	v_exp_f32_e32 v80, v80
	v_exp_f32_e32 v81, v81
	v_pk_add_f32 v[114:115], v[114:115], 1.0 op_sel_hi:[1,0]
	v_mul_f32_e32 v64, 0xbfb8aa3b, v64
	v_pk_add_f32 v[80:81], v[80:81], 1.0 op_sel_hi:[1,0]
	v_mul_f32_e32 v65, 0xbfb8aa3b, v65
	v_exp_f32_e32 v64, v64
	v_rcp_f32_e32 v113, v115
	s_nop 0
	v_exp_f32_e32 v65, v65
	v_mul_f32_e32 v48, 0xbfb8aa3b, v48
	v_mul_f32_e32 v49, 0xbfb8aa3b, v49
	v_rcp_f32_e32 v114, v114
	s_nop 0
	v_cvt_pk_bf16_f32 v113, v114, v113
	v_mul_f32_e32 v114, 0xbfb8aa3b, v116
	v_mul_f32_e32 v115, 0xbfb8aa3b, v117
	v_exp_f32_e32 v114, v114
	v_exp_f32_e32 v115, v115
	v_pk_add_f32 v[64:65], v[64:65], 1.0 op_sel_hi:[1,0]
	v_exp_f32_e32 v48, v48
	v_exp_f32_e32 v49, v49
	v_pk_add_f32 v[114:115], v[114:115], 1.0 op_sel_hi:[1,0]
	v_mul_f32_e32 v32, 0xbfb8aa3b, v32
	v_pk_add_f32 v[48:49], v[48:49], 1.0 op_sel_hi:[1,0]
	v_mul_f32_e32 v33, 0xbfb8aa3b, v33
	v_exp_f32_e32 v32, v32
	v_rcp_f32_e32 v115, v115
	s_nop 0
	v_exp_f32_e32 v33, v33
	v_mul_f32_e32 v16, 0xbfb8aa3b, v16
	v_mul_f32_e32 v17, 0xbfb8aa3b, v17
	v_rcp_f32_e32 v114, v114
	s_nop 0
	v_cvt_pk_bf16_f32 v114, v114, v115
	v_mul_f32_e32 v115, 0xbfb8aa3b, v118
	v_exp_f32_e32 v116, v115
	v_mul_f32_e32 v115, 0xbfb8aa3b, v119
	v_exp_f32_e32 v117, v115
	v_pk_add_f32 v[32:33], v[32:33], 1.0 op_sel_hi:[1,0]
	v_exp_f32_e32 v16, v16
	v_exp_f32_e32 v17, v17
	v_pk_add_f32 v[116:117], v[116:117], 1.0 op_sel_hi:[1,0]
	v_mul_f32_e32 v0, 0xbfb8aa3b, v0
	v_pk_add_f32 v[16:17], v[16:17], 1.0 op_sel_hi:[1,0]
	v_mul_f32_e32 v1, 0xbfb8aa3b, v1
	v_exp_f32_e32 v0, v0
	v_rcp_f32_e32 v115, v117
	s_nop 0
	v_exp_f32_e32 v1, v1
	s_mul_i32 s6, s6, 0x248000
	s_mul_hi_i32 s2, s2, 0x2480
	v_rcp_f32_e32 v116, v116
	s_nop 0
	v_cvt_pk_bf16_f32 v115, v116, v115
	ds_write2_b64 v128, v[112:113], v[114:115] offset1:2
	v_mul_f32_e32 v112, 0xbfb8aa3b, v120
	v_mul_f32_e32 v113, 0xbfb8aa3b, v121
	v_exp_f32_e32 v112, v112
	v_exp_f32_e32 v113, v113
	v_pk_add_f32 v[0:1], v[0:1], 1.0 op_sel_hi:[1,0]
	s_add_u32 s6, s4, s6
	s_addc_u32 s2, s5, s2
	v_pk_add_f32 v[112:113], v[112:113], 1.0 op_sel_hi:[1,0]
	s_ashr_i32 s9, s8, 31
	s_lshl_b64 s[4:5], s[8:9], 1
	s_add_u32 s4, s6, s4
	s_addc_u32 s5, s2, s5
	v_rcp_f32_e32 v113, v113
	s_nop 0
	s_nop 0
	v_rcp_f32_e32 v112, v112
	s_nop 0
	v_cvt_pk_bf16_f32 v112, v112, v113
	v_mul_f32_e32 v113, 0xbfb8aa3b, v122
	v_exp_f32_e32 v114, v113
	v_mul_f32_e32 v113, 0xbfb8aa3b, v123
	v_exp_f32_e32 v115, v113
	s_nop 0
	v_pk_add_f32 v[114:115], v[114:115], 1.0 op_sel_hi:[1,0]
	s_nop 0
	s_nop 0
	v_rcp_f32_e32 v113, v115
	s_nop 0
	s_nop 0
	v_rcp_f32_e32 v114, v114
	s_nop 0
	v_cvt_pk_bf16_f32 v113, v114, v113
	v_mul_f32_e32 v114, 0xbfb8aa3b, v124
	v_mul_f32_e32 v115, 0xbfb8aa3b, v125
	v_exp_f32_e32 v114, v114
	v_exp_f32_e32 v115, v115
	s_nop 0
	v_pk_add_f32 v[114:115], v[114:115], 1.0 op_sel_hi:[1,0]
	s_nop 0
	s_nop 0
	v_rcp_f32_e32 v115, v115
	s_nop 0
	s_nop 0
	v_rcp_f32_e32 v114, v114
	s_nop 0
	v_cvt_pk_bf16_f32 v114, v114, v115
	v_mul_f32_e32 v115, 0xbfb8aa3b, v126
	v_exp_f32_e32 v116, v115
	v_mul_f32_e32 v115, 0xbfb8aa3b, v127
	v_exp_f32_e32 v117, v115
	s_nop 0
	v_pk_add_f32 v[116:117], v[116:117], 1.0 op_sel_hi:[1,0]
	s_nop 0
	s_nop 0
	v_rcp_f32_e32 v115, v117
	s_nop 0
	s_nop 0
	v_rcp_f32_e32 v116, v116
	s_nop 0
	v_cvt_pk_bf16_f32 v115, v116, v115
	ds_write2_b64 v128, v[112:113], v[114:115] offset0:4 offset1:6
	s_nop 0
	v_rcp_f32_e32 v97, v97
	s_nop 0
	s_nop 0
	v_rcp_f32_e32 v96, v96
	s_nop 0
	v_cvt_pk_bf16_f32 v96, v96, v97
	v_mul_f32_e32 v97, 0xbfb8aa3b, v98
	v_exp_f32_e32 v98, v97
	v_mul_f32_e32 v97, 0xbfb8aa3b, v99
	v_exp_f32_e32 v99, v97
	s_nop 0
	v_pk_add_f32 v[98:99], v[98:99], 1.0 op_sel_hi:[1,0]
	s_nop 0
	s_nop 0
	v_rcp_f32_e32 v97, v99
	s_nop 0
	s_nop 0
	v_rcp_f32_e32 v98, v98
	s_nop 0
	v_cvt_pk_bf16_f32 v97, v98, v97
	v_mul_f32_e32 v98, 0xbfb8aa3b, v100
	v_mul_f32_e32 v99, 0xbfb8aa3b, v101
	v_exp_f32_e32 v98, v98
	v_exp_f32_e32 v99, v99
	s_nop 0
	v_pk_add_f32 v[98:99], v[98:99], 1.0 op_sel_hi:[1,0]
	s_nop 0
	s_nop 0
	v_rcp_f32_e32 v99, v99
	s_nop 0
	s_nop 0
	v_rcp_f32_e32 v98, v98
	s_nop 0
	v_cvt_pk_bf16_f32 v98, v98, v99
	v_mul_f32_e32 v99, 0xbfb8aa3b, v102
	v_exp_f32_e32 v100, v99
	v_mul_f32_e32 v99, 0xbfb8aa3b, v103
	v_exp_f32_e32 v101, v99
	s_nop 0
	v_pk_add_f32 v[100:101], v[100:101], 1.0 op_sel_hi:[1,0]
	s_nop 0
	s_nop 0
	v_rcp_f32_e32 v99, v101
	s_nop 0
	s_nop 0
	v_rcp_f32_e32 v100, v100
	s_nop 0
	v_cvt_pk_bf16_f32 v99, v100, v99
	v_add_u32_e32 v102, 0x2000, v128
	ds_write2_b64 v102, v[96:97], v[98:99] offset0:64 offset1:66
	v_mul_f32_e32 v96, 0xbfb8aa3b, v104
	v_mul_f32_e32 v97, 0xbfb8aa3b, v105
	v_exp_f32_e32 v96, v96
	v_exp_f32_e32 v97, v97
	s_nop 0
	v_pk_add_f32 v[96:97], v[96:97], 1.0 op_sel_hi:[1,0]
	s_nop 0
	s_nop 0
	v_rcp_f32_e32 v97, v97
	s_nop 0
	s_nop 0
	v_rcp_f32_e32 v96, v96
	s_nop 0
	v_cvt_pk_bf16_f32 v96, v96, v97
	v_mul_f32_e32 v97, 0xbfb8aa3b, v106
	v_exp_f32_e32 v98, v97
	v_mul_f32_e32 v97, 0xbfb8aa3b, v107
	v_exp_f32_e32 v99, v97
	s_nop 0
	v_pk_add_f32 v[98:99], v[98:99], 1.0 op_sel_hi:[1,0]
	s_nop 0
	s_nop 0
	v_rcp_f32_e32 v97, v99
	s_nop 0
	s_nop 0
	v_rcp_f32_e32 v98, v98
	s_nop 0
	v_cvt_pk_bf16_f32 v97, v98, v97
	v_mul_f32_e32 v98, 0xbfb8aa3b, v108
	v_mul_f32_e32 v99, 0xbfb8aa3b, v109
	v_exp_f32_e32 v98, v98
	v_exp_f32_e32 v99, v99
	s_nop 0
	v_pk_add_f32 v[98:99], v[98:99], 1.0 op_sel_hi:[1,0]
	s_nop 0
	s_nop 0
	v_rcp_f32_e32 v99, v99
	s_nop 0
	s_nop 0
	v_rcp_f32_e32 v98, v98
	s_nop 0
	v_cvt_pk_bf16_f32 v98, v98, v99
	v_mul_f32_e32 v99, 0xbfb8aa3b, v110
	v_exp_f32_e32 v100, v99
	v_mul_f32_e32 v99, 0xbfb8aa3b, v111
	v_exp_f32_e32 v101, v99
	s_nop 0
	v_pk_add_f32 v[100:101], v[100:101], 1.0 op_sel_hi:[1,0]
	s_nop 0
	s_nop 0
	v_rcp_f32_e32 v99, v101
	s_nop 0
	s_nop 0
	v_rcp_f32_e32 v100, v100
	s_nop 0
	v_cvt_pk_bf16_f32 v99, v100, v99
	ds_write2_b64 v102, v[96:97], v[98:99] offset0:68 offset1:70
	s_nop 0
	v_rcp_f32_e32 v81, v81
	s_nop 0
	s_nop 0
	v_rcp_f32_e32 v80, v80
	s_nop 0
	v_cvt_pk_bf16_f32 v80, v80, v81
	v_mul_f32_e32 v81, 0xbfb8aa3b, v82
	v_exp_f32_e32 v82, v81
	v_mul_f32_e32 v81, 0xbfb8aa3b, v83
	v_exp_f32_e32 v83, v81
	s_nop 0
	v_pk_add_f32 v[82:83], v[82:83], 1.0 op_sel_hi:[1,0]
	s_nop 0
	s_nop 0
	v_rcp_f32_e32 v81, v83
	s_nop 0
	s_nop 0
	v_rcp_f32_e32 v82, v82
	s_nop 0
	v_cvt_pk_bf16_f32 v81, v82, v81
	v_mul_f32_e32 v82, 0xbfb8aa3b, v84
	v_mul_f32_e32 v83, 0xbfb8aa3b, v85
	v_exp_f32_e32 v82, v82
	v_exp_f32_e32 v83, v83
	s_nop 0
	v_pk_add_f32 v[82:83], v[82:83], 1.0 op_sel_hi:[1,0]
	s_nop 0
	s_nop 0
	v_rcp_f32_e32 v83, v83
	s_nop 0
	s_nop 0
	v_rcp_f32_e32 v82, v82
	s_nop 0
	v_cvt_pk_bf16_f32 v82, v82, v83
	v_mul_f32_e32 v83, 0xbfb8aa3b, v86
	v_exp_f32_e32 v84, v83
	v_mul_f32_e32 v83, 0xbfb8aa3b, v87
	v_exp_f32_e32 v85, v83
	s_nop 0
	v_pk_add_f32 v[84:85], v[84:85], 1.0 op_sel_hi:[1,0]
	s_nop 0
	s_nop 0
	v_rcp_f32_e32 v83, v85
	s_nop 0
	s_nop 0
	v_rcp_f32_e32 v84, v84
	s_nop 0
	v_cvt_pk_bf16_f32 v83, v84, v83
	v_add_u32_e32 v86, 0x4000, v128
	ds_write2_b64 v86, v[80:81], v[82:83] offset0:128 offset1:130
	v_mul_f32_e32 v80, 0xbfb8aa3b, v88
	v_mul_f32_e32 v81, 0xbfb8aa3b, v89
	v_exp_f32_e32 v80, v80
	v_exp_f32_e32 v81, v81
	s_nop 0
	v_pk_add_f32 v[80:81], v[80:81], 1.0 op_sel_hi:[1,0]
	s_nop 0
	s_nop 0
	v_rcp_f32_e32 v81, v81
	s_nop 0
	s_nop 0
	v_rcp_f32_e32 v80, v80
	s_nop 0
	v_cvt_pk_bf16_f32 v80, v80, v81
	v_mul_f32_e32 v81, 0xbfb8aa3b, v90
	v_exp_f32_e32 v82, v81
	v_mul_f32_e32 v81, 0xbfb8aa3b, v91
	v_exp_f32_e32 v83, v81
	s_nop 0
	v_pk_add_f32 v[82:83], v[82:83], 1.0 op_sel_hi:[1,0]
	s_nop 0
	s_nop 0
	v_rcp_f32_e32 v81, v83
	s_nop 0
	s_nop 0
	v_rcp_f32_e32 v82, v82
	s_nop 0
	v_cvt_pk_bf16_f32 v81, v82, v81
	v_mul_f32_e32 v82, 0xbfb8aa3b, v92
	v_mul_f32_e32 v83, 0xbfb8aa3b, v93
	v_exp_f32_e32 v82, v82
	v_exp_f32_e32 v83, v83
	s_nop 0
	v_pk_add_f32 v[82:83], v[82:83], 1.0 op_sel_hi:[1,0]
	s_nop 0
	s_nop 0
	v_rcp_f32_e32 v83, v83
	s_nop 0
	s_nop 0
	v_rcp_f32_e32 v82, v82
	s_nop 0
	v_cvt_pk_bf16_f32 v82, v82, v83
	v_mul_f32_e32 v83, 0xbfb8aa3b, v94
	v_exp_f32_e32 v84, v83
	v_mul_f32_e32 v83, 0xbfb8aa3b, v95
	v_exp_f32_e32 v85, v83
	s_nop 0
	v_pk_add_f32 v[84:85], v[84:85], 1.0 op_sel_hi:[1,0]
	s_nop 0
	s_nop 0
	v_rcp_f32_e32 v83, v85
	s_nop 0
	s_nop 0
	v_rcp_f32_e32 v84, v84
	s_nop 0
	v_cvt_pk_bf16_f32 v83, v84, v83
	ds_write2_b64 v86, v[80:81], v[82:83] offset0:132 offset1:134
	s_nop 0
	v_rcp_f32_e32 v65, v65
	s_nop 0
	s_nop 0
	v_rcp_f32_e32 v64, v64
	s_nop 0
	v_cvt_pk_bf16_f32 v64, v64, v65
	v_mul_f32_e32 v65, 0xbfb8aa3b, v66
	v_exp_f32_e32 v66, v65
	v_mul_f32_e32 v65, 0xbfb8aa3b, v67
	v_exp_f32_e32 v67, v65
	s_nop 0
	v_pk_add_f32 v[66:67], v[66:67], 1.0 op_sel_hi:[1,0]
	s_nop 0
	s_nop 0
	v_rcp_f32_e32 v65, v67
	s_nop 0
	s_nop 0
	v_rcp_f32_e32 v66, v66
	s_nop 0
	v_cvt_pk_bf16_f32 v65, v66, v65
	v_mul_f32_e32 v66, 0xbfb8aa3b, v68
	v_mul_f32_e32 v67, 0xbfb8aa3b, v69
	v_exp_f32_e32 v66, v66
	v_exp_f32_e32 v67, v67
	s_nop 0
	v_pk_add_f32 v[66:67], v[66:67], 1.0 op_sel_hi:[1,0]
	s_nop 0
	s_nop 0
	v_rcp_f32_e32 v67, v67
	s_nop 0
	s_nop 0
	v_rcp_f32_e32 v66, v66
	s_nop 0
	v_cvt_pk_bf16_f32 v66, v66, v67
	v_mul_f32_e32 v67, 0xbfb8aa3b, v70
	v_exp_f32_e32 v68, v67
	v_mul_f32_e32 v67, 0xbfb8aa3b, v71
	v_exp_f32_e32 v69, v67
	s_nop 0
	v_pk_add_f32 v[68:69], v[68:69], 1.0 op_sel_hi:[1,0]
	s_nop 0
	s_nop 0
	v_rcp_f32_e32 v67, v69
	s_nop 0
	s_nop 0
	v_rcp_f32_e32 v68, v68
	s_nop 0
	v_cvt_pk_bf16_f32 v67, v68, v67
	v_add_u32_e32 v70, 0x6000, v128
	ds_write2_b64 v70, v[64:65], v[66:67] offset0:192 offset1:194
	v_mul_f32_e32 v64, 0xbfb8aa3b, v72
	v_mul_f32_e32 v65, 0xbfb8aa3b, v73
	v_exp_f32_e32 v64, v64
	v_exp_f32_e32 v65, v65
	s_nop 0
	v_pk_add_f32 v[64:65], v[64:65], 1.0 op_sel_hi:[1,0]
	s_nop 0
	s_nop 0
	v_rcp_f32_e32 v65, v65
	s_nop 0
	s_nop 0
	v_rcp_f32_e32 v64, v64
	s_nop 0
	v_cvt_pk_bf16_f32 v64, v64, v65
	v_mul_f32_e32 v65, 0xbfb8aa3b, v74
	v_exp_f32_e32 v66, v65
	v_mul_f32_e32 v65, 0xbfb8aa3b, v75
	v_exp_f32_e32 v67, v65
	s_nop 0
	v_pk_add_f32 v[66:67], v[66:67], 1.0 op_sel_hi:[1,0]
	s_nop 0
	s_nop 0
	v_rcp_f32_e32 v65, v67
	s_nop 0
	s_nop 0
	v_rcp_f32_e32 v66, v66
	s_nop 0
	v_cvt_pk_bf16_f32 v65, v66, v65
	v_mul_f32_e32 v66, 0xbfb8aa3b, v76
	v_mul_f32_e32 v67, 0xbfb8aa3b, v77
	v_exp_f32_e32 v66, v66
	v_exp_f32_e32 v67, v67
	s_nop 0
	v_pk_add_f32 v[66:67], v[66:67], 1.0 op_sel_hi:[1,0]
	s_nop 0
	s_nop 0
	v_rcp_f32_e32 v67, v67
	s_nop 0
	s_nop 0
	v_rcp_f32_e32 v66, v66
	s_nop 0
	v_cvt_pk_bf16_f32 v66, v66, v67
	v_mul_f32_e32 v67, 0xbfb8aa3b, v78
	v_exp_f32_e32 v68, v67
	v_mul_f32_e32 v67, 0xbfb8aa3b, v79
	v_exp_f32_e32 v69, v67
	s_nop 0
	v_pk_add_f32 v[68:69], v[68:69], 1.0 op_sel_hi:[1,0]
	s_nop 0
	s_nop 0
	v_rcp_f32_e32 v67, v69
	s_nop 0
	s_nop 0
	v_rcp_f32_e32 v68, v68
	s_nop 0
	v_cvt_pk_bf16_f32 v67, v68, v67
	ds_write2_b64 v70, v[64:65], v[66:67] offset0:196 offset1:198
	s_nop 0
	v_rcp_f32_e32 v49, v49
	s_nop 0
	s_nop 0
	v_rcp_f32_e32 v48, v48
	s_nop 0
	v_cvt_pk_bf16_f32 v48, v48, v49
	v_mul_f32_e32 v49, 0xbfb8aa3b, v50
	v_exp_f32_e32 v50, v49
	v_mul_f32_e32 v49, 0xbfb8aa3b, v51
	v_exp_f32_e32 v51, v49
	s_nop 0
	v_pk_add_f32 v[50:51], v[50:51], 1.0 op_sel_hi:[1,0]
	s_nop 0
	s_nop 0
	v_rcp_f32_e32 v49, v51
	s_nop 0
	s_nop 0
	v_rcp_f32_e32 v50, v50
	s_nop 0
	v_cvt_pk_bf16_f32 v49, v50, v49
	v_mul_f32_e32 v50, 0xbfb8aa3b, v52
	v_mul_f32_e32 v51, 0xbfb8aa3b, v53
	v_exp_f32_e32 v50, v50
	v_exp_f32_e32 v51, v51
	s_nop 0
	v_pk_add_f32 v[50:51], v[50:51], 1.0 op_sel_hi:[1,0]
	s_nop 0
	s_nop 0
	v_rcp_f32_e32 v51, v51
	s_nop 0
	s_nop 0
	v_rcp_f32_e32 v50, v50
	s_nop 0
	v_cvt_pk_bf16_f32 v50, v50, v51
	v_mul_f32_e32 v51, 0xbfb8aa3b, v54
	v_exp_f32_e32 v52, v51
	v_mul_f32_e32 v51, 0xbfb8aa3b, v55
	v_exp_f32_e32 v53, v51
	s_nop 0
	v_pk_add_f32 v[52:53], v[52:53], 1.0 op_sel_hi:[1,0]
	s_nop 0
	s_nop 0
	v_rcp_f32_e32 v51, v53
	s_nop 0
	s_nop 0
	v_rcp_f32_e32 v52, v52
	s_nop 0
	v_cvt_pk_bf16_f32 v51, v52, v51
	v_add_u32_e32 v54, 0x8800, v128
	ds_write2_b64 v54, v[48:49], v[50:51] offset1:2
	v_mul_f32_e32 v48, 0xbfb8aa3b, v56
	v_mul_f32_e32 v49, 0xbfb8aa3b, v57
	v_exp_f32_e32 v48, v48
	v_exp_f32_e32 v49, v49
	s_nop 0
	v_pk_add_f32 v[48:49], v[48:49], 1.0 op_sel_hi:[1,0]
	s_nop 0
	s_nop 0
	v_rcp_f32_e32 v49, v49
	s_nop 0
	s_nop 0
	v_rcp_f32_e32 v48, v48
	s_nop 0
	v_cvt_pk_bf16_f32 v48, v48, v49
	v_mul_f32_e32 v49, 0xbfb8aa3b, v58
	v_exp_f32_e32 v50, v49
	v_mul_f32_e32 v49, 0xbfb8aa3b, v59
	v_exp_f32_e32 v51, v49
	s_nop 0
	v_pk_add_f32 v[50:51], v[50:51], 1.0 op_sel_hi:[1,0]
	s_nop 0
	s_nop 0
	v_rcp_f32_e32 v49, v51
	s_nop 0
	s_nop 0
	v_rcp_f32_e32 v50, v50
	s_nop 0
	v_cvt_pk_bf16_f32 v49, v50, v49
	v_mul_f32_e32 v50, 0xbfb8aa3b, v60
	v_mul_f32_e32 v51, 0xbfb8aa3b, v61
	v_exp_f32_e32 v50, v50
	v_exp_f32_e32 v51, v51
	s_nop 0
	v_pk_add_f32 v[50:51], v[50:51], 1.0 op_sel_hi:[1,0]
	s_nop 0
	s_nop 0
	v_rcp_f32_e32 v51, v51
	s_nop 0
	s_nop 0
	v_rcp_f32_e32 v50, v50
	s_nop 0
	v_cvt_pk_bf16_f32 v50, v50, v51
	v_mul_f32_e32 v51, 0xbfb8aa3b, v62
	v_exp_f32_e32 v52, v51
	v_mul_f32_e32 v51, 0xbfb8aa3b, v63
	v_exp_f32_e32 v53, v51
	s_nop 0
	v_pk_add_f32 v[52:53], v[52:53], 1.0 op_sel_hi:[1,0]
	s_nop 0
	s_nop 0
	v_rcp_f32_e32 v51, v53
	s_nop 0
	s_nop 0
	v_rcp_f32_e32 v52, v52
	s_nop 0
	v_cvt_pk_bf16_f32 v51, v52, v51
	ds_write2_b64 v54, v[48:49], v[50:51] offset0:4 offset1:6
	s_nop 0
	v_rcp_f32_e32 v33, v33
	s_nop 0
	s_nop 0
	v_rcp_f32_e32 v32, v32
	s_nop 0
	v_cvt_pk_bf16_f32 v32, v32, v33
	v_mul_f32_e32 v33, 0xbfb8aa3b, v34
	v_exp_f32_e32 v34, v33
	v_mul_f32_e32 v33, 0xbfb8aa3b, v35
	v_exp_f32_e32 v35, v33
	s_nop 0
	v_pk_add_f32 v[34:35], v[34:35], 1.0 op_sel_hi:[1,0]
	s_nop 0
	s_nop 0
	v_rcp_f32_e32 v33, v35
	s_nop 0
	s_nop 0
	v_rcp_f32_e32 v34, v34
	s_nop 0
	v_cvt_pk_bf16_f32 v33, v34, v33
	v_mul_f32_e32 v34, 0xbfb8aa3b, v36
	v_mul_f32_e32 v35, 0xbfb8aa3b, v37
	v_exp_f32_e32 v34, v34
	v_exp_f32_e32 v35, v35
	s_nop 0
	v_pk_add_f32 v[34:35], v[34:35], 1.0 op_sel_hi:[1,0]
	s_nop 0
	s_nop 0
	v_rcp_f32_e32 v35, v35
	s_nop 0
	s_nop 0
	v_rcp_f32_e32 v34, v34
	s_nop 0
	v_cvt_pk_bf16_f32 v34, v34, v35
	v_mul_f32_e32 v35, 0xbfb8aa3b, v38
	v_exp_f32_e32 v36, v35
	v_mul_f32_e32 v35, 0xbfb8aa3b, v39
	v_exp_f32_e32 v37, v35
	s_nop 0
	v_pk_add_f32 v[36:37], v[36:37], 1.0 op_sel_hi:[1,0]
	s_nop 0
	s_nop 0
	v_rcp_f32_e32 v35, v37
	s_nop 0
	s_nop 0
	v_rcp_f32_e32 v36, v36
	s_nop 0
	v_cvt_pk_bf16_f32 v35, v36, v35
	v_add_u32_e32 v38, 0xa800, v128
	ds_write2_b64 v38, v[32:33], v[34:35] offset0:64 offset1:66
	v_mul_f32_e32 v32, 0xbfb8aa3b, v40
	v_mul_f32_e32 v33, 0xbfb8aa3b, v41
	v_exp_f32_e32 v32, v32
	v_exp_f32_e32 v33, v33
	s_nop 0
	v_pk_add_f32 v[32:33], v[32:33], 1.0 op_sel_hi:[1,0]
	s_nop 0
	s_nop 0
	v_rcp_f32_e32 v33, v33
	s_nop 0
	s_nop 0
	v_rcp_f32_e32 v32, v32
	s_nop 0
	v_cvt_pk_bf16_f32 v32, v32, v33
	v_mul_f32_e32 v33, 0xbfb8aa3b, v42
	v_exp_f32_e32 v34, v33
	v_mul_f32_e32 v33, 0xbfb8aa3b, v43
	v_exp_f32_e32 v35, v33
	s_nop 0
	v_pk_add_f32 v[34:35], v[34:35], 1.0 op_sel_hi:[1,0]
	s_nop 0
	s_nop 0
	v_rcp_f32_e32 v33, v35
	s_nop 0
	s_nop 0
	v_rcp_f32_e32 v34, v34
	s_nop 0
	v_cvt_pk_bf16_f32 v33, v34, v33
	v_mul_f32_e32 v34, 0xbfb8aa3b, v44
	v_mul_f32_e32 v35, 0xbfb8aa3b, v45
	v_exp_f32_e32 v34, v34
	v_exp_f32_e32 v35, v35
	s_nop 0
	v_pk_add_f32 v[34:35], v[34:35], 1.0 op_sel_hi:[1,0]
	s_nop 0
	s_nop 0
	v_rcp_f32_e32 v35, v35
	s_nop 0
	s_nop 0
	v_rcp_f32_e32 v34, v34
	s_nop 0
	v_cvt_pk_bf16_f32 v34, v34, v35
	v_mul_f32_e32 v35, 0xbfb8aa3b, v46
	v_exp_f32_e32 v36, v35
	v_mul_f32_e32 v35, 0xbfb8aa3b, v47
	v_exp_f32_e32 v37, v35
	s_nop 0
	v_pk_add_f32 v[36:37], v[36:37], 1.0 op_sel_hi:[1,0]
	s_nop 0
	s_nop 0
	v_rcp_f32_e32 v35, v37
	s_nop 0
	s_nop 0
	v_rcp_f32_e32 v36, v36
	s_nop 0
	v_cvt_pk_bf16_f32 v35, v36, v35
	ds_write2_b64 v38, v[32:33], v[34:35] offset0:68 offset1:70
	s_nop 0
	v_rcp_f32_e32 v17, v17
	s_nop 0
	s_nop 0
	v_rcp_f32_e32 v16, v16
	s_nop 0
	v_cvt_pk_bf16_f32 v16, v16, v17
	v_mul_f32_e32 v17, 0xbfb8aa3b, v18
	v_exp_f32_e32 v18, v17
	v_mul_f32_e32 v17, 0xbfb8aa3b, v19
	v_exp_f32_e32 v19, v17
	s_nop 0
	v_pk_add_f32 v[18:19], v[18:19], 1.0 op_sel_hi:[1,0]
	s_nop 0
	s_nop 0
	v_rcp_f32_e32 v17, v19
	s_nop 0
	s_nop 0
	v_rcp_f32_e32 v18, v18
	s_nop 0
	v_cvt_pk_bf16_f32 v17, v18, v17
	v_mul_f32_e32 v18, 0xbfb8aa3b, v20
	v_mul_f32_e32 v19, 0xbfb8aa3b, v21
	v_exp_f32_e32 v18, v18
	v_exp_f32_e32 v19, v19
	s_nop 0
	v_pk_add_f32 v[18:19], v[18:19], 1.0 op_sel_hi:[1,0]
	s_nop 0
	s_nop 0
	v_rcp_f32_e32 v19, v19
	s_nop 0
	s_nop 0
	v_rcp_f32_e32 v18, v18
	s_nop 0
	v_cvt_pk_bf16_f32 v18, v18, v19
	v_mul_f32_e32 v19, 0xbfb8aa3b, v22
	v_exp_f32_e32 v20, v19
	v_mul_f32_e32 v19, 0xbfb8aa3b, v23
	v_exp_f32_e32 v21, v19
	s_nop 0
	v_pk_add_f32 v[20:21], v[20:21], 1.0 op_sel_hi:[1,0]
	s_nop 0
	s_nop 0
	v_rcp_f32_e32 v19, v21
	s_nop 0
	s_nop 0
	v_rcp_f32_e32 v20, v20
	s_nop 0
	v_cvt_pk_bf16_f32 v19, v20, v19
	v_add_u32_e32 v22, 0xc800, v128
	ds_write2_b64 v22, v[16:17], v[18:19] offset0:128 offset1:130
	v_mul_f32_e32 v16, 0xbfb8aa3b, v24
	v_mul_f32_e32 v17, 0xbfb8aa3b, v25
	v_exp_f32_e32 v16, v16
	v_exp_f32_e32 v17, v17
	s_nop 0
	v_pk_add_f32 v[16:17], v[16:17], 1.0 op_sel_hi:[1,0]
	s_nop 0
	s_nop 0
	v_rcp_f32_e32 v17, v17
	s_nop 0
	s_nop 0
	v_rcp_f32_e32 v16, v16
	s_nop 0
	v_cvt_pk_bf16_f32 v16, v16, v17
	v_mul_f32_e32 v17, 0xbfb8aa3b, v26
	v_exp_f32_e32 v18, v17
	v_mul_f32_e32 v17, 0xbfb8aa3b, v27
	v_exp_f32_e32 v19, v17
	s_nop 0
	v_pk_add_f32 v[18:19], v[18:19], 1.0 op_sel_hi:[1,0]
	s_nop 0
	s_nop 0
	v_rcp_f32_e32 v17, v19
	s_nop 0
	s_nop 0
	v_rcp_f32_e32 v18, v18
	s_nop 0
	v_cvt_pk_bf16_f32 v17, v18, v17
	v_mul_f32_e32 v18, 0xbfb8aa3b, v28
	v_mul_f32_e32 v19, 0xbfb8aa3b, v29
	v_exp_f32_e32 v18, v18
	v_exp_f32_e32 v19, v19
	s_nop 0
	v_pk_add_f32 v[18:19], v[18:19], 1.0 op_sel_hi:[1,0]
	s_nop 0
	s_nop 0
	v_rcp_f32_e32 v19, v19
	s_nop 0
	s_nop 0
	v_rcp_f32_e32 v18, v18
	s_nop 0
	v_cvt_pk_bf16_f32 v18, v18, v19
	v_mul_f32_e32 v19, 0xbfb8aa3b, v30
	v_exp_f32_e32 v20, v19
	v_mul_f32_e32 v19, 0xbfb8aa3b, v31
	v_exp_f32_e32 v21, v19
	s_nop 0
	v_pk_add_f32 v[20:21], v[20:21], 1.0 op_sel_hi:[1,0]
	s_nop 0
	s_nop 0
	v_rcp_f32_e32 v19, v21
	s_nop 0
	s_nop 0
	v_rcp_f32_e32 v20, v20
	s_nop 0
	v_cvt_pk_bf16_f32 v19, v20, v19
	ds_write2_b64 v22, v[16:17], v[18:19] offset0:132 offset1:134
	s_nop 0
	v_rcp_f32_e32 v1, v1
	s_nop 0
	s_nop 0
	v_rcp_f32_e32 v0, v0
	s_nop 0
	v_cvt_pk_bf16_f32 v0, v0, v1
	v_mul_f32_e32 v1, 0xbfb8aa3b, v2
	v_exp_f32_e32 v2, v1
	v_mul_f32_e32 v1, 0xbfb8aa3b, v3
	v_exp_f32_e32 v3, v1
	s_nop 0
	v_pk_add_f32 v[2:3], v[2:3], 1.0 op_sel_hi:[1,0]
	s_nop 0
	s_nop 0
	v_rcp_f32_e32 v1, v3
	s_nop 0
	s_nop 0
	v_rcp_f32_e32 v2, v2
	s_nop 0
	v_cvt_pk_bf16_f32 v1, v2, v1
	v_mul_f32_e32 v2, 0xbfb8aa3b, v4
	v_mul_f32_e32 v3, 0xbfb8aa3b, v5
	v_exp_f32_e32 v2, v2
	v_exp_f32_e32 v3, v3
	s_nop 0
	v_pk_add_f32 v[2:3], v[2:3], 1.0 op_sel_hi:[1,0]
	s_nop 0
	s_nop 0
	v_rcp_f32_e32 v3, v3
	s_nop 0
	s_nop 0
	v_rcp_f32_e32 v2, v2
	s_nop 0
	v_cvt_pk_bf16_f32 v2, v2, v3
	v_mul_f32_e32 v3, 0xbfb8aa3b, v6
	v_exp_f32_e32 v4, v3
	v_mul_f32_e32 v3, 0xbfb8aa3b, v7
	v_exp_f32_e32 v5, v3
	s_nop 0
	v_pk_add_f32 v[4:5], v[4:5], 1.0 op_sel_hi:[1,0]
	s_nop 0
	s_nop 0
	v_rcp_f32_e32 v3, v5
	s_nop 0
	s_nop 0
	v_rcp_f32_e32 v4, v4
	s_nop 0
	v_cvt_pk_bf16_f32 v3, v4, v3
	v_add_u32_e32 v6, 0xe800, v128
	ds_write2_b64 v6, v[0:1], v[2:3] offset0:192 offset1:194
	v_mul_f32_e32 v0, 0xbfb8aa3b, v8
	v_mul_f32_e32 v1, 0xbfb8aa3b, v9
	v_exp_f32_e32 v0, v0
	v_exp_f32_e32 v1, v1
	s_nop 0
	v_pk_add_f32 v[0:1], v[0:1], 1.0 op_sel_hi:[1,0]
	s_nop 0
	s_nop 0
	v_rcp_f32_e32 v1, v1
	s_nop 0
	s_nop 0
	v_rcp_f32_e32 v0, v0
	s_nop 0
	v_cvt_pk_bf16_f32 v0, v0, v1
	v_mul_f32_e32 v1, 0xbfb8aa3b, v10
	v_exp_f32_e32 v2, v1
	v_mul_f32_e32 v1, 0xbfb8aa3b, v11
	v_exp_f32_e32 v3, v1
	s_nop 0
	v_pk_add_f32 v[2:3], v[2:3], 1.0 op_sel_hi:[1,0]
	s_nop 0
	s_nop 0
	v_rcp_f32_e32 v1, v3
	s_nop 0
	s_nop 0
	v_rcp_f32_e32 v2, v2
	s_nop 0
	v_cvt_pk_bf16_f32 v1, v2, v1
	v_mul_f32_e32 v2, 0xbfb8aa3b, v12
	v_mul_f32_e32 v3, 0xbfb8aa3b, v13
	v_exp_f32_e32 v2, v2
	v_exp_f32_e32 v3, v3
	s_nop 0
	v_pk_add_f32 v[2:3], v[2:3], 1.0 op_sel_hi:[1,0]
	s_nop 0
	s_nop 0
	v_rcp_f32_e32 v3, v3
	s_nop 0
	s_nop 0
	v_rcp_f32_e32 v2, v2
	s_nop 0
	v_cvt_pk_bf16_f32 v2, v2, v3
	v_mul_f32_e32 v3, 0xbfb8aa3b, v14
	v_exp_f32_e32 v4, v3
	v_mul_f32_e32 v3, 0xbfb8aa3b, v15
	v_exp_f32_e32 v5, v3
	s_nop 0
	v_pk_add_f32 v[4:5], v[4:5], 1.0 op_sel_hi:[1,0]
	s_nop 0
	s_nop 0
	v_rcp_f32_e32 v3, v5
	s_nop 0
	s_nop 0
	v_rcp_f32_e32 v4, v4
	s_nop 0
	v_cvt_pk_bf16_f32 v3, v4, v3
	v_mov_b32_e32 v10, v205
	ds_write2_b64 v6, v[0:1], v[2:3] offset0:196 offset1:198
	s_waitcnt lgkmcnt(0)
	s_barrier
	v_mov_b32_e32 v5, v129
	v_lshlrev_b32_e32 v0, 4, v10
	v_and_b32_e32 v4, 0xf0, v0
	v_lshl_add_u64 v[0:1], s[4:5], 0, v[4:5]
	s_mov_b64 s[4:5], 0x26a0000
	v_ashrrev_i32_e32 v5, 4, v10
	v_lshl_add_u64 v[6:7], v[0:1], 0, s[4:5]
	v_mad_u64_u32 v[0:1], s[4:5], v5, s47, v[4:5]
	v_mad_i64_i32 v[8:9], s[4:5], v5, s33, v[6:7]
	v_mov_b32_e32 v80, v0
	s_mov_b64 s[100:101], 0x24800
	ds_read_b128 v[16:19], v80
	ds_read_b128 v[20:23], v80 offset:4352
	ds_read_b128 v[24:27], v80 offset:8704
	ds_read_b128 v[28:31], v80 offset:13056
	ds_read_b128 v[32:35], v80 offset:17408
	ds_read_b128 v[36:39], v80 offset:21760
	ds_read_b128 v[40:43], v80 offset:26112
	ds_read_b128 v[44:47], v80 offset:30464
	ds_read_b128 v[48:51], v80 offset:34816
	ds_read_b128 v[52:55], v80 offset:39168
	ds_read_b128 v[56:59], v80 offset:43520
	ds_read_b128 v[60:63], v80 offset:47872
	ds_read_b128 v[64:67], v80 offset:52224
	ds_read_b128 v[68:71], v80 offset:56576
	ds_read_b128 v[72:75], v80 offset:60928
	ds_read_b128 v[76:79], v80 offset:65280
	s_waitcnt lgkmcnt(15)
	global_store_dwordx4 v[8:9], v[16:19], off
	v_lshl_add_u64 v[8:9], v[8:9], 0, s[100:101]
	s_waitcnt lgkmcnt(14)
	global_store_dwordx4 v[8:9], v[20:23], off
	v_lshl_add_u64 v[8:9], v[8:9], 0, s[100:101]
	s_waitcnt lgkmcnt(13)
	global_store_dwordx4 v[8:9], v[24:27], off
	v_lshl_add_u64 v[8:9], v[8:9], 0, s[100:101]
	s_waitcnt lgkmcnt(12)
	global_store_dwordx4 v[8:9], v[28:31], off
	v_lshl_add_u64 v[8:9], v[8:9], 0, s[100:101]
	s_waitcnt lgkmcnt(11)
	global_store_dwordx4 v[8:9], v[32:35], off
	v_lshl_add_u64 v[8:9], v[8:9], 0, s[100:101]
	s_waitcnt lgkmcnt(10)
	global_store_dwordx4 v[8:9], v[36:39], off
	v_lshl_add_u64 v[8:9], v[8:9], 0, s[100:101]
	s_waitcnt lgkmcnt(9)
	global_store_dwordx4 v[8:9], v[40:43], off
	v_lshl_add_u64 v[8:9], v[8:9], 0, s[100:101]
	s_waitcnt lgkmcnt(8)
	global_store_dwordx4 v[8:9], v[44:47], off
	v_lshl_add_u64 v[8:9], v[8:9], 0, s[100:101]
	s_waitcnt lgkmcnt(7)
	global_store_dwordx4 v[8:9], v[48:51], off
	v_lshl_add_u64 v[8:9], v[8:9], 0, s[100:101]
	s_waitcnt lgkmcnt(6)
	global_store_dwordx4 v[8:9], v[52:55], off
	v_lshl_add_u64 v[8:9], v[8:9], 0, s[100:101]
	s_waitcnt lgkmcnt(5)
	global_store_dwordx4 v[8:9], v[56:59], off
	v_lshl_add_u64 v[8:9], v[8:9], 0, s[100:101]
	s_waitcnt lgkmcnt(4)
	global_store_dwordx4 v[8:9], v[60:63], off
	v_lshl_add_u64 v[8:9], v[8:9], 0, s[100:101]
	s_waitcnt lgkmcnt(3)
	global_store_dwordx4 v[8:9], v[64:67], off
	v_lshl_add_u64 v[8:9], v[8:9], 0, s[100:101]
	s_waitcnt lgkmcnt(2)
	global_store_dwordx4 v[8:9], v[68:71], off
	v_lshl_add_u64 v[8:9], v[8:9], 0, s[100:101]
	s_waitcnt lgkmcnt(1)
	global_store_dwordx4 v[8:9], v[72:75], off
	v_lshl_add_u64 v[8:9], v[8:9], 0, s[100:101]
	s_waitcnt lgkmcnt(0)
	global_store_dwordx4 v[8:9], v[76:79], off

.LBB0_2050:
	v_mov_b32_e32 v128, v205
	s_waitcnt vmcnt(0)
	v_mov_b32_e32 v130, v205
	s_movk_i32 s2, 0xffe0
	v_and_b32_e32 v131, 31, v128
	v_ashrrev_i32_e32 v130, 2, v130
	v_lshrrev_b32_e32 v128, 2, v128
	v_lshlrev_b32_e32 v130, 1, v130
	v_and_b32_e32 v128, 8, v128
	v_and_or_b32 v128, v130, s2, v128
	v_mad_u32_u24 v128, v131, s53, v128
	v_mul_f32_e32 v130, 0xbfb8aa3b, v112
	v_mul_f32_e32 v131, 0xbfb8aa3b, v113
	v_exp_f32_e32 v130, v130
	v_exp_f32_e32 v131, v131
	s_mul_hi_i32 s2, s12, 0x248000
	s_mul_i32 s12, s12, 0x248000
	v_pk_add_f32 v[130:131], v[130:131], 1.0 op_sel_hi:[1,0]
	s_nop 0
	s_nop 0
	v_rcp_f32_e32 v132, v131
	s_nop 0
	v_mul_f32_e32 v113, v113, v132
	s_nop 0
	v_rcp_f32_e32 v131, v130
	s_nop 0
	v_mul_f32_e32 v112, v112, v131
	v_pk_mul_f32 v[112:113], v[120:121], v[112:113]
	s_nop 0
	v_cvt_pk_bf16_f32 v112, v112, v113
	v_mul_f32_e32 v113, 0xbfb8aa3b, v114
	v_exp_f32_e32 v120, v113
	v_mul_f32_e32 v113, 0xbfb8aa3b, v115
	v_exp_f32_e32 v121, v113
	s_nop 0
	v_pk_add_f32 v[120:121], v[120:121], 1.0 op_sel_hi:[1,0]
	s_nop 0
	s_nop 0
	v_rcp_f32_e32 v113, v121
	s_nop 0
	v_mul_f32_e32 v115, v115, v113
	s_nop 0
	v_rcp_f32_e32 v113, v120
	s_nop 0
	v_mul_f32_e32 v114, v114, v113
	v_pk_mul_f32 v[114:115], v[122:123], v[114:115]
	s_nop 0
	v_cvt_pk_bf16_f32 v113, v114, v115
	v_mul_f32_e32 v114, 0xbfb8aa3b, v116
	v_mul_f32_e32 v115, 0xbfb8aa3b, v117
	v_exp_f32_e32 v114, v114
	v_exp_f32_e32 v115, v115
	s_nop 0
	v_pk_add_f32 v[114:115], v[114:115], 1.0 op_sel_hi:[1,0]
	s_nop 0
	s_nop 0
	v_rcp_f32_e32 v120, v115
	s_nop 0
	v_mul_f32_e32 v115, v117, v120
	s_nop 0
	v_rcp_f32_e32 v117, v114
	s_nop 0
	v_mul_f32_e32 v114, v116, v117
	v_pk_mul_f32 v[114:115], v[124:125], v[114:115]
	s_nop 0
	v_cvt_pk_bf16_f32 v114, v114, v115
	v_mul_f32_e32 v115, 0xbfb8aa3b, v118
	v_exp_f32_e32 v116, v115
	v_mul_f32_e32 v115, 0xbfb8aa3b, v119
	v_exp_f32_e32 v117, v115
	s_nop 0
	v_pk_add_f32 v[116:117], v[116:117], 1.0 op_sel_hi:[1,0]
	s_nop 0
	s_nop 0
	v_rcp_f32_e32 v115, v117
	s_nop 0
	v_mul_f32_e32 v117, v119, v115
	s_nop 0
	v_rcp_f32_e32 v115, v116
	s_nop 0
	v_mul_f32_e32 v116, v118, v115
	v_pk_mul_f32 v[116:117], v[126:127], v[116:117]
	s_nop 0
	v_cvt_pk_bf16_f32 v115, v116, v117
	ds_write2_b64 v128, v[112:113], v[114:115] offset1:2
	v_mul_f32_e32 v112, 0xbfb8aa3b, v96
	v_mul_f32_e32 v113, 0xbfb8aa3b, v97
	v_exp_f32_e32 v112, v112
	v_exp_f32_e32 v113, v113
	s_nop 0
	v_pk_add_f32 v[112:113], v[112:113], 1.0 op_sel_hi:[1,0]
	s_nop 0
	s_nop 0
	v_rcp_f32_e32 v114, v113
	s_nop 0
	v_mul_f32_e32 v97, v97, v114
	s_nop 0
	v_rcp_f32_e32 v113, v112
	s_nop 0
	v_mul_f32_e32 v96, v96, v113
	v_pk_mul_f32 v[96:97], v[104:105], v[96:97]
	s_nop 0
	v_cvt_pk_bf16_f32 v96, v96, v97
	v_mul_f32_e32 v97, 0xbfb8aa3b, v98
	v_exp_f32_e32 v104, v97
	v_mul_f32_e32 v97, 0xbfb8aa3b, v99
	v_exp_f32_e32 v105, v97
	s_nop 0
	v_pk_add_f32 v[104:105], v[104:105], 1.0 op_sel_hi:[1,0]
	s_nop 0
	s_nop 0
	v_rcp_f32_e32 v97, v105
	s_nop 0
	v_mul_f32_e32 v99, v99, v97
	s_nop 0
	v_rcp_f32_e32 v97, v104
	s_nop 0
	v_mul_f32_e32 v98, v98, v97
	v_pk_mul_f32 v[98:99], v[106:107], v[98:99]
	s_nop 0
	v_cvt_pk_bf16_f32 v97, v98, v99
	v_mul_f32_e32 v98, 0xbfb8aa3b, v100
	v_mul_f32_e32 v99, 0xbfb8aa3b, v101
	v_exp_f32_e32 v98, v98
	v_exp_f32_e32 v99, v99
	s_nop 0
	v_pk_add_f32 v[98:99], v[98:99], 1.0 op_sel_hi:[1,0]
	s_nop 0
	s_nop 0
	v_rcp_f32_e32 v104, v99
	s_nop 0
	v_mul_f32_e32 v99, v101, v104
	s_nop 0
	v_rcp_f32_e32 v101, v98
	s_nop 0
	v_mul_f32_e32 v98, v100, v101
	v_pk_mul_f32 v[98:99], v[108:109], v[98:99]
	s_nop 0
	v_cvt_pk_bf16_f32 v98, v98, v99
	v_mul_f32_e32 v99, 0xbfb8aa3b, v102
	v_exp_f32_e32 v100, v99
	v_mul_f32_e32 v99, 0xbfb8aa3b, v103
	v_exp_f32_e32 v101, v99
	s_nop 0
	v_pk_add_f32 v[100:101], v[100:101], 1.0 op_sel_hi:[1,0]
	s_nop 0
	s_nop 0
	v_rcp_f32_e32 v99, v101
	s_nop 0
	v_mul_f32_e32 v101, v103, v99
	s_nop 0
	v_rcp_f32_e32 v99, v100
	s_nop 0
	v_mul_f32_e32 v100, v102, v99
	v_pk_mul_f32 v[100:101], v[110:111], v[100:101]
	s_nop 0
	v_cvt_pk_bf16_f32 v99, v100, v101
	v_add_u32_e32 v100, 0x1000, v128
	ds_write2_b64 v100, v[96:97], v[98:99] offset0:64 offset1:66
	v_mul_f32_e32 v96, 0xbfb8aa3b, v80
	v_mul_f32_e32 v97, 0xbfb8aa3b, v81
	v_exp_f32_e32 v96, v96
	v_exp_f32_e32 v97, v97
	s_nop 0
	v_pk_add_f32 v[96:97], v[96:97], 1.0 op_sel_hi:[1,0]
	s_nop 0
	s_nop 0
	v_rcp_f32_e32 v98, v97
	s_nop 0
	v_mul_f32_e32 v81, v81, v98
	s_nop 0
	v_rcp_f32_e32 v97, v96
	s_nop 0
	v_mul_f32_e32 v80, v80, v97
	v_pk_mul_f32 v[80:81], v[88:89], v[80:81]
	s_nop 0
	v_cvt_pk_bf16_f32 v80, v80, v81
	v_mul_f32_e32 v81, 0xbfb8aa3b, v82
	v_exp_f32_e32 v88, v81
	v_mul_f32_e32 v81, 0xbfb8aa3b, v83
	v_exp_f32_e32 v89, v81
	s_nop 0
	v_pk_add_f32 v[88:89], v[88:89], 1.0 op_sel_hi:[1,0]
	s_nop 0
	s_nop 0
	v_rcp_f32_e32 v81, v89
	s_nop 0
	v_mul_f32_e32 v83, v83, v81
	s_nop 0
	v_rcp_f32_e32 v81, v88
	s_nop 0
	v_mul_f32_e32 v82, v82, v81
	v_pk_mul_f32 v[82:83], v[90:91], v[82:83]
	s_nop 0
	v_cvt_pk_bf16_f32 v81, v82, v83
	v_mul_f32_e32 v82, 0xbfb8aa3b, v84
	v_mul_f32_e32 v83, 0xbfb8aa3b, v85
	v_exp_f32_e32 v82, v82
	v_exp_f32_e32 v83, v83
	s_nop 0
	v_pk_add_f32 v[82:83], v[82:83], 1.0 op_sel_hi:[1,0]
	s_nop 0
	s_nop 0
	v_rcp_f32_e32 v88, v83
	s_nop 0
	v_mul_f32_e32 v83, v85, v88
	s_nop 0
	v_rcp_f32_e32 v85, v82
	s_nop 0
	v_mul_f32_e32 v82, v84, v85
	v_pk_mul_f32 v[82:83], v[92:93], v[82:83]
	s_nop 0
	v_cvt_pk_bf16_f32 v82, v82, v83
	v_mul_f32_e32 v83, 0xbfb8aa3b, v86
	v_exp_f32_e32 v84, v83
	v_mul_f32_e32 v83, 0xbfb8aa3b, v87
	v_exp_f32_e32 v85, v83
	s_nop 0
	v_pk_add_f32 v[84:85], v[84:85], 1.0 op_sel_hi:[1,0]
	s_nop 0
	s_nop 0
	v_rcp_f32_e32 v83, v85
	s_nop 0
	v_mul_f32_e32 v85, v87, v83
	s_nop 0
	v_rcp_f32_e32 v83, v84
	s_nop 0
	v_mul_f32_e32 v84, v86, v83
	v_pk_mul_f32 v[84:85], v[94:95], v[84:85]
	s_nop 0
	v_cvt_pk_bf16_f32 v83, v84, v85
	v_add_u32_e32 v84, 0x2000, v128
	ds_write2_b64 v84, v[80:81], v[82:83] offset0:128 offset1:130
	v_mul_f32_e32 v80, 0xbfb8aa3b, v64
	v_mul_f32_e32 v81, 0xbfb8aa3b, v65
	v_exp_f32_e32 v80, v80
	v_exp_f32_e32 v81, v81
	s_nop 0
	v_pk_add_f32 v[80:81], v[80:81], 1.0 op_sel_hi:[1,0]
	s_nop 0
	s_nop 0
	v_rcp_f32_e32 v82, v81
	s_nop 0
	v_mul_f32_e32 v65, v65, v82
	s_nop 0
	v_rcp_f32_e32 v81, v80
	s_nop 0
	v_mul_f32_e32 v64, v64, v81
	v_pk_mul_f32 v[64:65], v[72:73], v[64:65]
	s_nop 0
	v_cvt_pk_bf16_f32 v64, v64, v65
	v_mul_f32_e32 v65, 0xbfb8aa3b, v66
	v_exp_f32_e32 v72, v65
	v_mul_f32_e32 v65, 0xbfb8aa3b, v67
	v_exp_f32_e32 v73, v65
	s_nop 0
	v_pk_add_f32 v[72:73], v[72:73], 1.0 op_sel_hi:[1,0]
	s_nop 0
	s_nop 0
	v_rcp_f32_e32 v65, v73
	s_nop 0
	v_mul_f32_e32 v67, v67, v65
	s_nop 0
	v_rcp_f32_e32 v65, v72
	s_nop 0
	v_mul_f32_e32 v66, v66, v65
	v_pk_mul_f32 v[66:67], v[74:75], v[66:67]
	s_nop 0
	v_cvt_pk_bf16_f32 v65, v66, v67
	v_mul_f32_e32 v66, 0xbfb8aa3b, v68
	v_mul_f32_e32 v67, 0xbfb8aa3b, v69
	v_exp_f32_e32 v66, v66
	v_exp_f32_e32 v67, v67
	s_nop 0
	v_pk_add_f32 v[66:67], v[66:67], 1.0 op_sel_hi:[1,0]
	s_nop 0
	s_nop 0
	v_rcp_f32_e32 v72, v67
	s_nop 0
	v_mul_f32_e32 v67, v69, v72
	s_nop 0
	v_rcp_f32_e32 v69, v66
	s_nop 0
	v_mul_f32_e32 v66, v68, v69
	v_pk_mul_f32 v[66:67], v[76:77], v[66:67]
	s_nop 0
	v_cvt_pk_bf16_f32 v66, v66, v67
	v_mul_f32_e32 v67, 0xbfb8aa3b, v70
	v_exp_f32_e32 v68, v67
	v_mul_f32_e32 v67, 0xbfb8aa3b, v71
	v_exp_f32_e32 v69, v67
	s_nop 0
	v_pk_add_f32 v[68:69], v[68:69], 1.0 op_sel_hi:[1,0]
	s_nop 0
	s_nop 0
	v_rcp_f32_e32 v67, v69
	s_nop 0
	v_mul_f32_e32 v69, v71, v67
	s_nop 0
	v_rcp_f32_e32 v67, v68
	s_nop 0
	v_mul_f32_e32 v68, v70, v67
	v_pk_mul_f32 v[68:69], v[78:79], v[68:69]
	s_nop 0
	v_cvt_pk_bf16_f32 v67, v68, v69
	v_add_u32_e32 v68, 0x3000, v128
	ds_write2_b64 v68, v[64:65], v[66:67] offset0:192 offset1:194
	v_mul_f32_e32 v64, 0xbfb8aa3b, v48
	v_mul_f32_e32 v65, 0xbfb8aa3b, v49
	v_exp_f32_e32 v64, v64
	v_exp_f32_e32 v65, v65
	s_nop 0
	v_pk_add_f32 v[64:65], v[64:65], 1.0 op_sel_hi:[1,0]
	s_nop 0
	s_nop 0
	v_rcp_f32_e32 v66, v65
	s_nop 0
	v_mul_f32_e32 v49, v49, v66
	s_nop 0
	v_rcp_f32_e32 v65, v64
	s_nop 0
	v_mul_f32_e32 v48, v48, v65
	v_pk_mul_f32 v[48:49], v[56:57], v[48:49]
	s_nop 0
	v_cvt_pk_bf16_f32 v48, v48, v49
	v_mul_f32_e32 v49, 0xbfb8aa3b, v50
	v_exp_f32_e32 v56, v49
	v_mul_f32_e32 v49, 0xbfb8aa3b, v51
	v_exp_f32_e32 v57, v49
	s_nop 0
	v_pk_add_f32 v[56:57], v[56:57], 1.0 op_sel_hi:[1,0]
	s_nop 0
	s_nop 0
	v_rcp_f32_e32 v49, v57
	s_nop 0
	v_mul_f32_e32 v51, v51, v49
	s_nop 0
	v_rcp_f32_e32 v49, v56
	s_nop 0
	v_mul_f32_e32 v50, v50, v49
	v_pk_mul_f32 v[50:51], v[58:59], v[50:51]
	s_nop 0
	v_cvt_pk_bf16_f32 v49, v50, v51
	v_mul_f32_e32 v50, 0xbfb8aa3b, v52
	v_mul_f32_e32 v51, 0xbfb8aa3b, v53
	v_exp_f32_e32 v50, v50
	v_exp_f32_e32 v51, v51
	s_nop 0
	v_pk_add_f32 v[50:51], v[50:51], 1.0 op_sel_hi:[1,0]
	s_nop 0
	s_nop 0
	v_rcp_f32_e32 v56, v51
	s_nop 0
	v_mul_f32_e32 v51, v53, v56
	s_nop 0
	v_rcp_f32_e32 v53, v50
	s_nop 0
	v_mul_f32_e32 v50, v52, v53
	v_pk_mul_f32 v[50:51], v[60:61], v[50:51]
	s_nop 0
	v_cvt_pk_bf16_f32 v50, v50, v51
	v_mul_f32_e32 v51, 0xbfb8aa3b, v54
	v_exp_f32_e32 v52, v51
	v_mul_f32_e32 v51, 0xbfb8aa3b, v55
	v_exp_f32_e32 v53, v51
	s_nop 0
	v_pk_add_f32 v[52:53], v[52:53], 1.0 op_sel_hi:[1,0]
	s_nop 0
	s_nop 0
	v_rcp_f32_e32 v51, v53
	s_nop 0
	v_mul_f32_e32 v53, v55, v51
	s_nop 0
	v_rcp_f32_e32 v51, v52
	s_nop 0
	v_mul_f32_e32 v52, v54, v51
	v_pk_mul_f32 v[52:53], v[62:63], v[52:53]
	s_nop 0
	v_cvt_pk_bf16_f32 v51, v52, v53
	v_add_u32_e32 v52, 0x4800, v128
	ds_write2_b64 v52, v[48:49], v[50:51] offset1:2
	v_mul_f32_e32 v48, 0xbfb8aa3b, v32
	v_mul_f32_e32 v49, 0xbfb8aa3b, v33
	v_exp_f32_e32 v48, v48
	v_exp_f32_e32 v49, v49
	s_nop 0
	v_pk_add_f32 v[48:49], v[48:49], 1.0 op_sel_hi:[1,0]
	s_nop 0
	s_nop 0
	v_rcp_f32_e32 v50, v49
	s_nop 0
	v_mul_f32_e32 v33, v33, v50
	s_nop 0
	v_rcp_f32_e32 v49, v48
	s_nop 0
	v_mul_f32_e32 v32, v32, v49
	v_pk_mul_f32 v[32:33], v[40:41], v[32:33]
	s_nop 0
	v_cvt_pk_bf16_f32 v32, v32, v33
	v_mul_f32_e32 v33, 0xbfb8aa3b, v34
	v_exp_f32_e32 v40, v33
	v_mul_f32_e32 v33, 0xbfb8aa3b, v35
	v_exp_f32_e32 v41, v33
	s_nop 0
	v_pk_add_f32 v[40:41], v[40:41], 1.0 op_sel_hi:[1,0]
	s_nop 0
	s_nop 0
	v_rcp_f32_e32 v33, v41
	s_nop 0
	v_mul_f32_e32 v35, v35, v33
	s_nop 0
	v_rcp_f32_e32 v33, v40
	s_nop 0
	v_mul_f32_e32 v34, v34, v33
	v_pk_mul_f32 v[34:35], v[42:43], v[34:35]
	s_nop 0
	v_cvt_pk_bf16_f32 v33, v34, v35
	v_mul_f32_e32 v34, 0xbfb8aa3b, v36
	v_mul_f32_e32 v35, 0xbfb8aa3b, v37
	v_exp_f32_e32 v34, v34
	v_exp_f32_e32 v35, v35
	s_nop 0
	v_pk_add_f32 v[34:35], v[34:35], 1.0 op_sel_hi:[1,0]
	s_nop 0
	s_nop 0
	v_rcp_f32_e32 v40, v35
	s_nop 0
	v_mul_f32_e32 v35, v37, v40
	s_nop 0
	v_rcp_f32_e32 v37, v34
	s_nop 0
	v_mul_f32_e32 v34, v36, v37
	v_pk_mul_f32 v[34:35], v[44:45], v[34:35]
	s_nop 0
	v_cvt_pk_bf16_f32 v34, v34, v35
	v_mul_f32_e32 v35, 0xbfb8aa3b, v38
	v_exp_f32_e32 v36, v35
	v_mul_f32_e32 v35, 0xbfb8aa3b, v39
	v_exp_f32_e32 v37, v35
	s_nop 0
	v_pk_add_f32 v[36:37], v[36:37], 1.0 op_sel_hi:[1,0]
	s_nop 0
	s_nop 0
	v_rcp_f32_e32 v35, v37
	s_nop 0
	v_mul_f32_e32 v37, v39, v35
	s_nop 0
	v_rcp_f32_e32 v35, v36
	s_nop 0
	v_mul_f32_e32 v36, v38, v35
	v_pk_mul_f32 v[36:37], v[46:47], v[36:37]
	s_nop 0
	v_cvt_pk_bf16_f32 v35, v36, v37
	v_add_u32_e32 v36, 0x5800, v128
	ds_write2_b64 v36, v[32:33], v[34:35] offset0:64 offset1:66
	v_mul_f32_e32 v32, 0xbfb8aa3b, v16
	v_mul_f32_e32 v33, 0xbfb8aa3b, v17
	v_exp_f32_e32 v32, v32
	v_exp_f32_e32 v33, v33
	s_nop 0
	v_pk_add_f32 v[32:33], v[32:33], 1.0 op_sel_hi:[1,0]
	s_nop 0
	s_nop 0
	v_rcp_f32_e32 v34, v33
	s_nop 0
	v_mul_f32_e32 v17, v17, v34
	s_nop 0
	v_rcp_f32_e32 v33, v32
	s_nop 0
	v_mul_f32_e32 v16, v16, v33
	v_pk_mul_f32 v[16:17], v[24:25], v[16:17]
	s_nop 0
	v_cvt_pk_bf16_f32 v16, v16, v17
	v_mul_f32_e32 v17, 0xbfb8aa3b, v18
	v_exp_f32_e32 v24, v17
	v_mul_f32_e32 v17, 0xbfb8aa3b, v19
	v_exp_f32_e32 v25, v17
	s_nop 0
	v_pk_add_f32 v[24:25], v[24:25], 1.0 op_sel_hi:[1,0]
	s_nop 0
	s_nop 0
	v_rcp_f32_e32 v17, v25
	s_nop 0
	v_mul_f32_e32 v19, v19, v17
	s_nop 0
	v_rcp_f32_e32 v17, v24
	s_nop 0
	v_mul_f32_e32 v18, v18, v17
	v_pk_mul_f32 v[18:19], v[26:27], v[18:19]
	s_nop 0
	v_cvt_pk_bf16_f32 v17, v18, v19
	v_mul_f32_e32 v18, 0xbfb8aa3b, v20
	v_mul_f32_e32 v19, 0xbfb8aa3b, v21
	v_exp_f32_e32 v18, v18
	v_exp_f32_e32 v19, v19
	s_nop 0
	v_pk_add_f32 v[18:19], v[18:19], 1.0 op_sel_hi:[1,0]
	s_nop 0
	s_nop 0
	v_rcp_f32_e32 v24, v19
	s_nop 0
	v_mul_f32_e32 v19, v21, v24
	s_nop 0
	v_rcp_f32_e32 v21, v18
	s_nop 0
	v_mul_f32_e32 v18, v20, v21
	v_pk_mul_f32 v[18:19], v[28:29], v[18:19]
	s_nop 0
	v_cvt_pk_bf16_f32 v18, v18, v19
	v_mul_f32_e32 v19, 0xbfb8aa3b, v22
	v_exp_f32_e32 v20, v19
	v_mul_f32_e32 v19, 0xbfb8aa3b, v23
	v_exp_f32_e32 v21, v19
	s_nop 0
	v_pk_add_f32 v[20:21], v[20:21], 1.0 op_sel_hi:[1,0]
	s_nop 0
	s_nop 0
	v_rcp_f32_e32 v19, v21
	s_nop 0
	v_mul_f32_e32 v21, v23, v19
	s_nop 0
	v_rcp_f32_e32 v19, v20
	s_nop 0
	v_mul_f32_e32 v20, v22, v19
	v_pk_mul_f32 v[20:21], v[30:31], v[20:21]
	s_nop 0
	v_cvt_pk_bf16_f32 v19, v20, v21
	v_add_u32_e32 v20, 0x6800, v128
	ds_write2_b64 v20, v[16:17], v[18:19] offset0:128 offset1:130
	v_mul_f32_e32 v16, 0xbfb8aa3b, v0
	v_mul_f32_e32 v17, 0xbfb8aa3b, v1
	v_exp_f32_e32 v16, v16
	v_exp_f32_e32 v17, v17
	s_nop 0
	v_pk_add_f32 v[16:17], v[16:17], 1.0 op_sel_hi:[1,0]
	s_nop 0
	s_nop 0
	v_rcp_f32_e32 v18, v17
	s_nop 0
	v_mul_f32_e32 v1, v1, v18
	s_nop 0
	v_rcp_f32_e32 v17, v16
	s_nop 0
	v_mul_f32_e32 v0, v0, v17
	v_pk_mul_f32 v[0:1], v[8:9], v[0:1]
	s_nop 0
	v_cvt_pk_bf16_f32 v0, v0, v1
	v_mul_f32_e32 v1, 0xbfb8aa3b, v2
	v_exp_f32_e32 v8, v1
	v_mul_f32_e32 v1, 0xbfb8aa3b, v3
	v_exp_f32_e32 v9, v1
	s_nop 0
	v_pk_add_f32 v[8:9], v[8:9], 1.0 op_sel_hi:[1,0]
	s_nop 0
	s_nop 0
	v_rcp_f32_e32 v1, v9
	s_nop 0
	v_mul_f32_e32 v3, v3, v1
	s_nop 0
	v_rcp_f32_e32 v1, v8
	s_nop 0
	v_mul_f32_e32 v2, v2, v1
	v_pk_mul_f32 v[2:3], v[10:11], v[2:3]
	s_nop 0
	v_cvt_pk_bf16_f32 v1, v2, v3
	v_mul_f32_e32 v2, 0xbfb8aa3b, v4
	v_mul_f32_e32 v3, 0xbfb8aa3b, v5
	v_exp_f32_e32 v2, v2
	v_exp_f32_e32 v3, v3
	s_nop 0
	v_pk_add_f32 v[2:3], v[2:3], 1.0 op_sel_hi:[1,0]
	s_nop 0
	s_nop 0
	v_rcp_f32_e32 v8, v3
	s_nop 0
	v_mul_f32_e32 v3, v5, v8
	s_nop 0
	v_rcp_f32_e32 v5, v2
	s_nop 0
	v_mul_f32_e32 v2, v4, v5
	v_pk_mul_f32 v[2:3], v[12:13], v[2:3]
	s_nop 0
	v_cvt_pk_bf16_f32 v2, v2, v3
	v_mul_f32_e32 v3, 0xbfb8aa3b, v6
	v_exp_f32_e32 v4, v3
	v_mul_f32_e32 v3, 0xbfb8aa3b, v7
	v_exp_f32_e32 v5, v3
	s_nop 0
	v_pk_add_f32 v[4:5], v[4:5], 1.0 op_sel_hi:[1,0]
	s_nop 0
	s_nop 0
	v_rcp_f32_e32 v3, v5
	s_nop 0
	v_mul_f32_e32 v5, v7, v3
	s_add_u32 s14, s19, s12
	s_addc_u32 s2, s20, s2
	s_lshl_b32 s12, s23, 6
	v_rcp_f32_e32 v3, v4
	s_nop 0
	v_mul_f32_e32 v4, v6, v3
	v_pk_mul_f32 v[4:5], v[14:15], v[4:5]
	s_ashr_i32 s13, s12, 31
	v_cvt_pk_bf16_f32 v3, v4, v5
	v_add_u32_e32 v4, 0x7800, v128
	s_lshl_b64 s[12:13], s[12:13], 1
	v_mov_b32_e32 v10, v205
	ds_write2_b64 v4, v[0:1], v[2:3] offset0:192 offset1:194
	s_waitcnt lgkmcnt(0)
	s_barrier
	s_add_u32 s12, s14, s12
	s_addc_u32 s13, s2, s13
	v_lshlrev_b32_e32 v0, 4, v10
	v_and_b32_e32 v4, 0x70, v0
	v_mov_b32_e32 v5, v129
	v_lshl_add_u64 v[6:7], s[12:13], 0, v[4:5]
	v_ashrrev_i32_e32 v5, 3, v10
	v_mad_u64_u32 v[0:1], s[12:13], v5, s53, v[4:5]
	v_mad_i64_i32 v[8:9], s[12:13], v5, s33, v[6:7]
	v_mov_b32_e32 v80, v0
	s_mov_b64 s[100:101], 0x49000
	ds_read_b128 v[16:19], v80
	ds_read_b128 v[20:23], v80 offset:4608
	ds_read_b128 v[24:27], v80 offset:9216
	ds_read_b128 v[28:31], v80 offset:13824
	ds_read_b128 v[32:35], v80 offset:18432
	ds_read_b128 v[36:39], v80 offset:23040
	ds_read_b128 v[40:43], v80 offset:27648
	ds_read_b128 v[44:47], v80 offset:32256
	s_waitcnt lgkmcnt(7)
	global_store_dwordx4 v[8:9], v[16:19], off
	v_lshl_add_u64 v[8:9], v[8:9], 0, s[100:101]
	s_waitcnt lgkmcnt(6)
	global_store_dwordx4 v[8:9], v[20:23], off
	v_lshl_add_u64 v[8:9], v[8:9], 0, s[100:101]
	s_waitcnt lgkmcnt(5)
	global_store_dwordx4 v[8:9], v[24:27], off
	v_lshl_add_u64 v[8:9], v[8:9], 0, s[100:101]
	s_waitcnt lgkmcnt(4)
	global_store_dwordx4 v[8:9], v[28:31], off
	v_lshl_add_u64 v[8:9], v[8:9], 0, s[100:101]
	s_waitcnt lgkmcnt(3)
	global_store_dwordx4 v[8:9], v[32:35], off
	v_lshl_add_u64 v[8:9], v[8:9], 0, s[100:101]
	s_waitcnt lgkmcnt(2)
	global_store_dwordx4 v[8:9], v[36:39], off
	v_lshl_add_u64 v[8:9], v[8:9], 0, s[100:101]
	s_waitcnt lgkmcnt(1)
	global_store_dwordx4 v[8:9], v[40:43], off
	v_lshl_add_u64 v[8:9], v[8:9], 0, s[100:101]
	s_waitcnt lgkmcnt(0)
	global_store_dwordx4 v[8:9], v[44:47], off

.LBB0_2180:
	s_mov_b64 s[4:5], s[0:1]
	v_mov_b32_e32 v0, v205
	s_lshl_b32 s2, s61, 2
	s_movk_i32 s3, 0x5000
	v_ashrrev_i32_e32 v2, 6, v205
	v_add_u32_e32 v4, s2, v2
	v_cmp_gt_i32_e32 vcc, s3, v4
	s_and_saveexec_b64 s[6:7], vcc
	s_cbranch_execz .LBB0_2183
	v_and_b32_e32 v1, 64, v216
	v_add_u32_e32 v1, 64, v1
	v_xor_b32_e32 v3, 1, v216
	v_cmp_lt_i32_e32 vcc, v3, v1
	s_load_dwordx2 s[6:7], s[4:5], 0x100
	s_load_dwordx2 s[8:9], s[0:1], 0xf8
	v_cndmask_b32_e32 v3, v216, v3, vcc
	v_lshlrev_b32_e32 v5, 2, v3
	v_xor_b32_e32 v3, 2, v216
	v_cmp_lt_i32_e32 vcc, v3, v1
	s_ashr_i32 s3, s2, 31
	v_lshlrev_b32_e32 v0, 4, v0
	v_cndmask_b32_e32 v3, v216, v3, vcc
	v_lshlrev_b32_e32 v6, 2, v3
	v_xor_b32_e32 v3, 4, v216
	v_cmp_lt_i32_e32 vcc, v3, v1
	v_and_b32_e32 v12, 0x3f0, v0
	v_mov_b32_e32 v13, 0
	v_cndmask_b32_e32 v3, v216, v3, vcc
	v_lshlrev_b32_e32 v7, 2, v3
	v_xor_b32_e32 v3, 8, v216
	v_cmp_lt_i32_e32 vcc, v3, v1
	s_mov_b64 s[0:1], 0xc00
	v_mov_b32_e32 v11, 0x358637bd
	v_cndmask_b32_e32 v3, v216, v3, vcc
	v_lshlrev_b32_e32 v8, 2, v3
	v_xor_b32_e32 v3, 16, v216
	v_cmp_lt_i32_e32 vcc, v3, v1
	s_nop 1
	v_cndmask_b32_e32 v3, v216, v3, vcc
	v_lshlrev_b32_e32 v9, 2, v3
	v_xor_b32_e32 v3, 32, v216
	v_cmp_lt_i32_e32 vcc, v3, v1
	s_nop 1
	v_cndmask_b32_e32 v1, v216, v3, vcc
	v_ashrrev_i32_e32 v3, 31, v2
	v_lshl_add_u64 v[2:3], v[2:3], 0, s[2:3]
	v_lshlrev_b64 v[2:3], 12, v[2:3]
	v_or_b32_e32 v2, v2, v12
	s_waitcnt lgkmcnt(0)
	v_lshl_add_u64 v[2:3], s[6:7], 0, v[2:3]
	v_lshlrev_b32_e32 v10, 2, v1
	v_lshl_add_u64 v[0:1], s[8:9], 0, v[12:13]
	v_lshl_add_u64 v[2:3], v[2:3], 0, s[0:1]
	s_mov_b64 s[0:1], 0
	s_mov_b32 s2, 0x800000
	s_movk_i32 s3, 0x4fff
	global_load_dwordx4 v[130:133], v[0:1], off offset:1024
	global_load_dwordx4 v[134:137], v[0:1], off offset:2048
	global_load_dwordx4 v[138:141], v[0:1], off offset:3072
	s_waitcnt vmcnt(0)
.LBB0_2182:
	global_load_dwordx4 v[12:15], v[2:3], off offset:-3072
	global_load_dwordx4 v[16:19], v[2:3], off offset:-2048
	global_load_dwordx4 v[20:23], v[2:3], off offset:-1024
	global_load_dwordx4 v[24:27], v[2:3], off
	global_load_dwordx4 v[28:31], v[0:1], off
	v_add_u32_e32 v4, s66, v4
	s_waitcnt vmcnt(4)
	v_mov_b32_e32 v34, v13
	s_waitcnt vmcnt(3)
	v_mov_b32_e32 v35, v17
	v_mov_b32_e32 v32, v12
	v_mov_b32_e32 v33, v16
	s_waitcnt vmcnt(2)
	v_mov_b32_e32 v42, v21
	s_waitcnt vmcnt(1)
	v_mov_b32_e32 v43, v25
	v_pk_mul_f32 v[34:35], v[34:35], v[34:35]
	v_mov_b32_e32 v36, v14
	v_mov_b32_e32 v37, v18
	v_mov_b32_e32 v40, v20
	v_mov_b32_e32 v41, v24
	v_pk_mul_f32 v[42:43], v[42:43], v[42:43]
	v_pk_fma_f32 v[32:33], v[32:33], v[32:33], v[34:35]
	v_mov_b32_e32 v38, v15
	v_mov_b32_e32 v39, v19
	v_mov_b32_e32 v44, v22
	v_mov_b32_e32 v45, v26
	v_pk_fma_f32 v[34:35], v[40:41], v[40:41], v[42:43]
	v_pk_fma_f32 v[32:33], v[36:37], v[36:37], v[32:33]
	v_mov_b32_e32 v46, v23
	v_mov_b32_e32 v47, v27
	v_pk_fma_f32 v[34:35], v[44:45], v[44:45], v[34:35]
	v_pk_fma_f32 v[32:33], v[38:39], v[38:39], v[32:33]
	v_pk_fma_f32 v[34:35], v[46:47], v[46:47], v[34:35]
	v_add_f32_e32 v32, v32, v33
	v_add_f32_e32 v32, v32, v34
	v_add_f32_e32 v32, v32, v35
	ds_bpermute_b32 v33, v5, v32
	s_waitcnt lgkmcnt(0)
	v_add_f32_e32 v32, v32, v33
	ds_bpermute_b32 v33, v6, v32
	s_waitcnt lgkmcnt(0)
	v_add_f32_e32 v32, v32, v33
	ds_bpermute_b32 v33, v7, v32
	s_waitcnt lgkmcnt(0)
	v_add_f32_e32 v32, v32, v33
	ds_bpermute_b32 v33, v8, v32
	s_waitcnt lgkmcnt(0)
	v_add_f32_e32 v32, v32, v33
	ds_bpermute_b32 v33, v9, v32
	s_waitcnt lgkmcnt(0)
	v_add_f32_e32 v32, v32, v33
	ds_bpermute_b32 v33, v10, v32
	s_waitcnt lgkmcnt(0)
	v_add_f32_e32 v32, v32, v33
	v_fmamk_f32 v32, v32, 0x3a800000, v11
	v_mul_f32_e32 v33, 0x4b800000, v32
	v_cmp_gt_f32_e32 vcc, s2, v32
	s_nop 1
	v_cndmask_b32_e32 v32, v32, v33, vcc
	v_rsq_f32_e32 v32, v32
	s_nop 0
	v_mul_f32_e32 v33, 0x45800000, v32
	v_cndmask_b32_e32 v32, v32, v33, vcc
	v_pk_mul_f32 v[12:13], v[12:13], v[32:33] op_sel_hi:[1,0]
	v_pk_mul_f32 v[14:15], v[14:15], v[32:33] op_sel_hi:[1,0]
	s_waitcnt vmcnt(0)
	v_pk_mul_f32 v[12:13], v[28:29], v[12:13]
	v_pk_mul_f32 v[14:15], v[30:31], v[14:15]
	global_store_dwordx4 v[2:3], v[12:15], off offset:-3072
	v_pk_mul_f32 v[18:19], v[18:19], v[32:33] op_sel_hi:[1,0]
	v_pk_mul_f32 v[16:17], v[16:17], v[32:33] op_sel_hi:[1,0]
	v_cmp_lt_i32_e32 vcc, s3, v4
	s_or_b64 s[0:1], vcc, s[0:1]
	v_pk_mul_f32 v[12:13], v[130:131], v[16:17]
	v_pk_mul_f32 v[14:15], v[132:133], v[18:19]
	global_store_dwordx4 v[2:3], v[12:15], off offset:-2048
	v_pk_mul_f32 v[16:17], v[22:23], v[32:33] op_sel_hi:[1,0]
	v_pk_mul_f32 v[18:19], v[20:21], v[32:33] op_sel_hi:[1,0]
	v_pk_mul_f32 v[14:15], v[136:137], v[16:17]
	v_pk_mul_f32 v[12:13], v[134:135], v[18:19]
	global_store_dwordx4 v[2:3], v[12:15], off offset:-1024
	v_pk_mul_f32 v[16:17], v[26:27], v[32:33] op_sel_hi:[1,0]
	v_pk_mul_f32 v[18:19], v[24:25], v[32:33] op_sel_hi:[1,0]
	v_pk_mul_f32 v[14:15], v[140:141], v[16:17]
	v_pk_mul_f32 v[12:13], v[138:139], v[18:19]
	global_store_dwordx4 v[2:3], v[12:15], off
	v_lshl_add_u64 v[2:3], v[2:3], 0, s[76:77]
	s_andn2_b64 exec, exec, s[0:1]
	s_cbranch_execnz .LBB0_2182
